# out-proj and ff2 epilogues: residual loads hoisted with counted waits, LDS-DMA stage issued after them (on top of stagger0, S1 half MFMA, ptfill, quadstage)
# speedup vs baseline: 1.0121x; 1.0121x over previous
.LBB0_844:
	s_add_i32 s98, s0, 0x40080
	s_mov_b32 s8, s70
	v_mov_b32_e32 v175, v237
	v_mov_b32_e32 v130, v236
	s_lshl_b32 s0, s27, 8
	s_or_b32 s0, s0, s51
	v_add_u32_e32 v146, s50, v130
	v_lshl_add_u32 v130, v175, 3, s0
	s_lshl_b32 s0, s43, 10
	v_lshl_add_u32 v170, s26, 8, v146
	s_add_i32 s0, s0, 0
	v_add_u32_e32 v132, 0x80, v170
	v_ashrrev_i32_e32 v171, 31, v170
	v_lshl_add_u32 v146, v146, 2, s0
	v_ashrrev_i32_e32 v133, 31, v132
	v_ashrrev_i32_e32 v131, 31, v130
	v_add_u32_e32 v174, 0x20100, v146
	v_lshlrev_b64 v[146:147], 11, v[170:171]
	v_lshlrev_b64 v[132:133], 11, v[132:133]
	v_lshlrev_b64 v[172:173], 1, v[130:131]
	v_lshl_add_u64 v[146:147], s[74:75], 0, v[146:147]
	v_lshl_add_u64 v[132:133], s[74:75], 0, v[132:133]
	v_lshl_add_u64 v[134:135], v[130:131], 2, s[76:77]
	v_lshl_add_u64 v[152:153], v[146:147], 0, v[172:173]
	v_lshl_add_u64 v[230:231], v[132:133], 0, v[172:173]
	global_load_dwordx4 v[138:141], v[134:135], off offset:16
	global_load_dwordx4 v[142:145], v[134:135], off
	global_load_dwordx4 v[130:133], v[134:135], off offset:528
	s_nop 0
	global_load_dwordx4 v[134:137], v[134:135], off offset:512
	ds_read_b32 v150, v174
	v_lshl_add_u32 v251, v170, 11, v172
	global_load_dwordx4 v[202:205], v251, s[74:75]
	global_load_dwordx4 v[206:209], v251, s[74:75] offset:256
	v_add_u32_e32 v251, 0x8000, v251
	global_load_dwordx4 v[210:213], v251, s[74:75]
	global_load_dwordx4 v[214:217], v251, s[74:75] offset:256
	v_add_u32_e32 v251, 0x8000, v251
	global_load_dwordx4 v[218:221], v251, s[74:75]
	global_load_dwordx4 v[222:225], v251, s[74:75] offset:256
	s_mov_b32 m0, s52
	s_nop 0
	buffer_load_dwordx4 v1, s[8:11], s98 offen lds
	s_mov_b32 m0, s53
	s_nop 0
	buffer_load_dwordx4 v234, s[8:11], s98 offen lds
	s_mov_b64 s[4:5], 0
	s_waitcnt vmcnt(7)
	v_lshlrev_b32_e32 v154, 16, v202
	v_and_b32_e32 v155, 0xffff0000, v202
	v_lshlrev_b32_e32 v146, 16, v203
	v_and_b32_e32 v147, 0xffff0000, v203
	v_lshlrev_b32_e32 v156, 16, v204
	v_and_b32_e32 v157, 0xffff0000, v204
	v_lshlrev_b32_e32 v148, 16, v205
	v_and_b32_e32 v149, 0xffff0000, v205
	s_waitcnt lgkmcnt(0)
	v_pk_mul_f32 v[146:147], v[150:151], v[146:147] op_sel_hi:[0,1]
	v_pk_mul_f32 v[154:155], v[150:151], v[154:155] op_sel_hi:[0,1]
	v_pk_fma_f32 v[158:159], v[144:145], v[146:147], v[76:77]
	v_pk_mul_f32 v[146:147], v[150:151], v[156:157] op_sel_hi:[0,1]
	v_pk_mul_f32 v[148:149], v[150:151], v[148:149] op_sel_hi:[0,1]
	v_pk_fma_f32 v[154:155], v[142:143], v[154:155], v[74:75]
	v_pk_fma_f32 v[156:157], v[140:141], v[148:149], v[72:73]
	v_pk_fma_f32 v[160:161], v[138:139], v[146:147], v[70:71]
	v_cvt_pk_bf16_f32 v146, v154, v155
	v_cvt_pk_bf16_f32 v147, v158, v159
	v_pk_mul_f32 v[158:159], v[158:159], v[158:159]
	v_cvt_pk_bf16_f32 v148, v160, v161
	v_cvt_pk_bf16_f32 v149, v156, v157
	global_store_dwordx4 v[152:153], v[146:149], off
	v_add_u32_e32 v251, 0x8000, v251
	global_load_dwordx4 v[202:205], v251, s[74:75]
	v_pk_mul_f32 v[154:155], v[154:155], v[154:155]
	v_pk_fma_f32 v[156:157], v[156:157], v[156:157], v[158:159]
	v_pk_fma_f32 v[154:155], v[160:161], v[160:161], v[154:155]
	s_waitcnt vmcnt(8)
	v_lshlrev_b32_e32 v158, 16, v206
	v_and_b32_e32 v159, 0xffff0000, v206
	v_lshlrev_b32_e32 v146, 16, v207
	v_and_b32_e32 v147, 0xffff0000, v207
	v_lshlrev_b32_e32 v160, 16, v208
	v_and_b32_e32 v161, 0xffff0000, v208
	v_lshlrev_b32_e32 v148, 16, v209
	v_and_b32_e32 v149, 0xffff0000, v209
	v_pk_mul_f32 v[146:147], v[150:151], v[146:147] op_sel_hi:[0,1]
	v_pk_mul_f32 v[158:159], v[150:151], v[158:159] op_sel_hi:[0,1]
	v_pk_fma_f32 v[162:163], v[136:137], v[146:147], v[100:101]
	v_pk_mul_f32 v[146:147], v[150:151], v[160:161] op_sel_hi:[0,1]
	v_pk_mul_f32 v[148:149], v[150:151], v[148:149] op_sel_hi:[0,1]
	v_pk_fma_f32 v[158:159], v[134:135], v[158:159], v[98:99]
	v_pk_fma_f32 v[150:151], v[132:133], v[148:149], v[96:97]
	v_pk_fma_f32 v[160:161], v[130:131], v[146:147], v[94:95]
	v_cvt_pk_bf16_f32 v146, v158, v159
	v_cvt_pk_bf16_f32 v147, v162, v163
	s_nop 0
	v_cvt_pk_bf16_f32 v148, v160, v161
	v_cvt_pk_bf16_f32 v149, v150, v151
	global_store_dwordx4 v[152:153], v[146:149], off offset:256
	s_nop 1
	v_pk_fma_f32 v[146:147], v[162:163], v[162:163], v[156:157]
	v_pk_fma_f32 v[148:149], v[158:159], v[158:159], v[154:155]
	v_pk_fma_f32 v[146:147], v[150:151], v[150:151], v[146:147]
	v_pk_fma_f32 v[148:149], v[160:161], v[160:161], v[148:149]
	s_nop 0
	v_pk_mov_b32 v[150:151], v[148:149], v[146:147] op_sel:[1,0]
	v_mov_b32_e32 v149, v147
	v_pk_add_f32 v[146:147], v[150:151], v[148:149]
	v_and_b32_e32 v148, 64, v250
	v_add_f32_e32 v146, v146, v147
	v_xor_b32_e32 v147, 16, v250
	v_add_u32_e32 v148, 64, v148
	v_cmp_lt_i32_e32 vcc, v147, v148
	ds_read_b32 v150, v174 offset:64
	s_nop 0
	v_cndmask_b32_e32 v147, v250, v147, vcc
	v_lshlrev_b32_e32 v178, 2, v147
	ds_bpermute_b32 v147, v178, v146
	s_waitcnt lgkmcnt(0)
	v_add_f32_e32 v171, v146, v147
	v_xor_b32_e32 v146, 32, v250
	v_cmp_lt_i32_e32 vcc, v146, v148
	s_nop 1
	v_cndmask_b32_e32 v146, v250, v146, vcc
	v_lshlrev_b32_e32 v177, 2, v146
	v_add_u32_e32 v146, 16, v170
	v_ashrrev_i32_e32 v147, 31, v146
	v_lshlrev_b64 v[146:147], 11, v[146:147]
	v_lshl_add_u64 v[146:147], s[74:75], 0, v[146:147]
	v_lshl_add_u64 v[152:153], v[146:147], 0, v[172:173]
	global_load_dwordx4 v[206:209], v251, s[74:75] offset:256
	ds_bpermute_b32 v176, v177, v171
	v_cmp_lt_i32_e32 vcc, 0, v175
	s_waitcnt vmcnt(9)
	v_lshlrev_b32_e32 v154, 16, v210
	v_and_b32_e32 v155, 0xffff0000, v210
	v_lshlrev_b32_e32 v146, 16, v211
	v_and_b32_e32 v147, 0xffff0000, v211
	v_lshlrev_b32_e32 v156, 16, v212
	v_and_b32_e32 v157, 0xffff0000, v212
	v_lshlrev_b32_e32 v148, 16, v213
	v_and_b32_e32 v149, 0xffff0000, v213
	v_pk_mul_f32 v[146:147], v[150:151], v[146:147] op_sel_hi:[0,1]
	v_pk_mul_f32 v[154:155], v[150:151], v[154:155] op_sel_hi:[0,1]
	v_pk_fma_f32 v[158:159], v[144:145], v[146:147], v[68:69]
	v_pk_mul_f32 v[146:147], v[150:151], v[156:157] op_sel_hi:[0,1]
	v_pk_mul_f32 v[148:149], v[150:151], v[148:149] op_sel_hi:[0,1]
	v_pk_fma_f32 v[154:155], v[142:143], v[154:155], v[66:67]
	v_pk_fma_f32 v[156:157], v[140:141], v[148:149], v[84:85]
	v_pk_fma_f32 v[160:161], v[138:139], v[146:147], v[82:83]
	v_cvt_pk_bf16_f32 v146, v154, v155
	v_cvt_pk_bf16_f32 v147, v158, v159
	v_pk_mul_f32 v[158:159], v[158:159], v[158:159]
	v_cvt_pk_bf16_f32 v148, v160, v161
	v_cvt_pk_bf16_f32 v149, v156, v157
	global_store_dwordx4 v[152:153], v[146:149], off
	v_add_u32_e32 v251, 0x28000, v251
	global_load_dwordx4 v[210:213], v251, s[74:75]
	v_pk_mul_f32 v[154:155], v[154:155], v[154:155]
	v_pk_fma_f32 v[156:157], v[156:157], v[156:157], v[158:159]
	v_pk_fma_f32 v[154:155], v[160:161], v[160:161], v[154:155]
	s_waitcnt vmcnt(10)
	v_lshlrev_b32_e32 v158, 16, v214
	v_and_b32_e32 v159, 0xffff0000, v214
	v_lshlrev_b32_e32 v146, 16, v215
	v_and_b32_e32 v147, 0xffff0000, v215
	v_lshlrev_b32_e32 v160, 16, v216
	v_and_b32_e32 v161, 0xffff0000, v216
	v_lshlrev_b32_e32 v148, 16, v217
	v_and_b32_e32 v149, 0xffff0000, v217
	v_pk_mul_f32 v[146:147], v[150:151], v[146:147] op_sel_hi:[0,1]
	v_pk_mul_f32 v[158:159], v[150:151], v[158:159] op_sel_hi:[0,1]
	v_pk_fma_f32 v[162:163], v[136:137], v[146:147], v[108:109]
	v_pk_mul_f32 v[146:147], v[150:151], v[160:161] op_sel_hi:[0,1]
	v_pk_mul_f32 v[148:149], v[150:151], v[148:149] op_sel_hi:[0,1]
	v_pk_fma_f32 v[158:159], v[134:135], v[158:159], v[106:107]
	v_pk_fma_f32 v[150:151], v[132:133], v[148:149], v[112:113]
	v_pk_fma_f32 v[160:161], v[130:131], v[146:147], v[110:111]
	v_cvt_pk_bf16_f32 v146, v158, v159
	v_cvt_pk_bf16_f32 v147, v162, v163
	s_nop 0
	v_cvt_pk_bf16_f32 v148, v160, v161
	v_cvt_pk_bf16_f32 v149, v150, v151
	global_store_dwordx4 v[152:153], v[146:149], off offset:256
	s_nop 1
	v_pk_fma_f32 v[146:147], v[162:163], v[162:163], v[156:157]
	v_pk_fma_f32 v[148:149], v[158:159], v[158:159], v[154:155]
	v_pk_fma_f32 v[146:147], v[150:151], v[150:151], v[146:147]
	v_pk_fma_f32 v[148:149], v[160:161], v[160:161], v[148:149]
	v_add_f32_e32 v146, v146, v147
	v_add_f32_e32 v148, v148, v149
	v_add_f32_e32 v146, v148, v146
	ds_bpermute_b32 v147, v178, v146
	ds_read_b32 v150, v174 offset:128
	s_waitcnt lgkmcnt(1)
	v_add_f32_e32 v179, v146, v147
	v_add_u32_e32 v146, 32, v170
	v_ashrrev_i32_e32 v147, 31, v146
	v_lshlrev_b64 v[146:147], 11, v[146:147]
	v_lshl_add_u64 v[146:147], s[74:75], 0, v[146:147]
	v_lshl_add_u64 v[152:153], v[146:147], 0, v[172:173]
	global_load_dwordx4 v[214:217], v251, s[74:75] offset:256
	ds_bpermute_b32 v180, v177, v179
	s_waitcnt vmcnt(11)
	v_lshlrev_b32_e32 v154, 16, v218
	v_and_b32_e32 v155, 0xffff0000, v218
	v_lshlrev_b32_e32 v146, 16, v219
	v_and_b32_e32 v147, 0xffff0000, v219
	v_lshlrev_b32_e32 v156, 16, v220
	v_and_b32_e32 v157, 0xffff0000, v220
	v_lshlrev_b32_e32 v148, 16, v221
	v_and_b32_e32 v149, 0xffff0000, v221
	s_waitcnt lgkmcnt(1)
	v_pk_mul_f32 v[146:147], v[150:151], v[146:147] op_sel_hi:[0,1]
	v_pk_mul_f32 v[154:155], v[150:151], v[154:155] op_sel_hi:[0,1]
	v_pk_fma_f32 v[158:159], v[144:145], v[146:147], v[80:81]
	v_pk_mul_f32 v[146:147], v[150:151], v[156:157] op_sel_hi:[0,1]
	v_pk_mul_f32 v[148:149], v[150:151], v[148:149] op_sel_hi:[0,1]
	v_pk_fma_f32 v[154:155], v[142:143], v[154:155], v[78:79]
	v_pk_fma_f32 v[156:157], v[140:141], v[148:149], v[92:93]
	v_pk_fma_f32 v[160:161], v[138:139], v[146:147], v[90:91]
	v_cvt_pk_bf16_f32 v146, v154, v155
	v_cvt_pk_bf16_f32 v147, v158, v159
	v_pk_mul_f32 v[158:159], v[158:159], v[158:159]
	v_cvt_pk_bf16_f32 v148, v160, v161
	v_cvt_pk_bf16_f32 v149, v156, v157
	global_store_dwordx4 v[152:153], v[146:149], off
	v_add_u32_e32 v251, 0x8000, v251
	global_load_dwordx4 v[218:221], v251, s[74:75]
	v_pk_mul_f32 v[154:155], v[154:155], v[154:155]
	v_pk_fma_f32 v[156:157], v[156:157], v[156:157], v[158:159]
	v_pk_fma_f32 v[154:155], v[160:161], v[160:161], v[154:155]
	s_waitcnt vmcnt(12)
	v_lshlrev_b32_e32 v158, 16, v222
	v_and_b32_e32 v159, 0xffff0000, v222
	v_lshlrev_b32_e32 v146, 16, v223
	v_and_b32_e32 v147, 0xffff0000, v223
	v_lshlrev_b32_e32 v160, 16, v224
	v_and_b32_e32 v161, 0xffff0000, v224
	v_lshlrev_b32_e32 v148, 16, v225
	v_and_b32_e32 v149, 0xffff0000, v225
	v_pk_mul_f32 v[146:147], v[150:151], v[146:147] op_sel_hi:[0,1]
	v_pk_mul_f32 v[158:159], v[150:151], v[158:159] op_sel_hi:[0,1]
	v_pk_fma_f32 v[162:163], v[136:137], v[146:147], v[116:117]
	v_pk_mul_f32 v[146:147], v[150:151], v[160:161] op_sel_hi:[0,1]
	v_pk_mul_f32 v[148:149], v[150:151], v[148:149] op_sel_hi:[0,1]
	v_pk_fma_f32 v[158:159], v[134:135], v[158:159], v[114:115]
	v_pk_fma_f32 v[150:151], v[132:133], v[148:149], v[120:121]
	v_pk_fma_f32 v[160:161], v[130:131], v[146:147], v[118:119]
	v_cvt_pk_bf16_f32 v146, v158, v159
	v_cvt_pk_bf16_f32 v147, v162, v163
	s_nop 0
	v_cvt_pk_bf16_f32 v148, v160, v161
	v_cvt_pk_bf16_f32 v149, v150, v151
	global_store_dwordx4 v[152:153], v[146:149], off offset:256
	s_nop 1
	v_pk_fma_f32 v[146:147], v[162:163], v[162:163], v[156:157]
	v_pk_fma_f32 v[148:149], v[158:159], v[158:159], v[154:155]
	v_pk_fma_f32 v[146:147], v[150:151], v[150:151], v[146:147]
	v_pk_fma_f32 v[148:149], v[160:161], v[160:161], v[148:149]
	v_add_f32_e32 v146, v146, v147
	v_add_f32_e32 v148, v148, v149
	v_add_f32_e32 v146, v148, v146
	ds_bpermute_b32 v147, v178, v146
	ds_read_b32 v150, v174 offset:192
	s_waitcnt lgkmcnt(1)
	v_add_f32_e32 v181, v146, v147
	v_add_u32_e32 v146, 48, v170
	v_ashrrev_i32_e32 v147, 31, v146
	v_lshlrev_b64 v[146:147], 11, v[146:147]
	v_lshl_add_u64 v[146:147], s[74:75], 0, v[146:147]
	v_lshl_add_u64 v[152:153], v[146:147], 0, v[172:173]
	global_load_dwordx4 v[222:225], v251, s[74:75] offset:256
	ds_bpermute_b32 v182, v177, v181
	s_waitcnt vmcnt(10)
	v_lshlrev_b32_e32 v154, 16, v202
	v_and_b32_e32 v155, 0xffff0000, v202
	v_lshlrev_b32_e32 v146, 16, v203
	v_and_b32_e32 v147, 0xffff0000, v203
	v_lshlrev_b32_e32 v156, 16, v204
	v_and_b32_e32 v157, 0xffff0000, v204
	v_lshlrev_b32_e32 v148, 16, v205
	v_and_b32_e32 v149, 0xffff0000, v205
	s_waitcnt lgkmcnt(1)
	v_pk_mul_f32 v[146:147], v[150:151], v[146:147] op_sel_hi:[0,1]
	v_pk_mul_f32 v[154:155], v[150:151], v[154:155] op_sel_hi:[0,1]
	v_pk_fma_f32 v[158:159], v[144:145], v[146:147], v[88:89]
	v_pk_mul_f32 v[146:147], v[150:151], v[156:157] op_sel_hi:[0,1]
	v_pk_mul_f32 v[148:149], v[150:151], v[148:149] op_sel_hi:[0,1]
	v_pk_fma_f32 v[154:155], v[142:143], v[154:155], v[86:87]
	v_pk_fma_f32 v[156:157], v[140:141], v[148:149], v[104:105]
	v_pk_fma_f32 v[160:161], v[138:139], v[146:147], v[102:103]
	v_cvt_pk_bf16_f32 v146, v154, v155
	v_cvt_pk_bf16_f32 v147, v158, v159
	v_pk_mul_f32 v[158:159], v[158:159], v[158:159]
	v_cvt_pk_bf16_f32 v148, v160, v161
	v_cvt_pk_bf16_f32 v149, v156, v157
	global_store_dwordx4 v[152:153], v[146:149], off
	v_add_u32_e32 v251, 0x8000, v251
	global_load_dwordx4 v[202:205], v251, s[74:75]
	v_pk_mul_f32 v[154:155], v[154:155], v[154:155]
	v_pk_fma_f32 v[156:157], v[156:157], v[156:157], v[158:159]
	v_pk_fma_f32 v[154:155], v[160:161], v[160:161], v[154:155]
	s_waitcnt vmcnt(10)
	v_lshlrev_b32_e32 v158, 16, v206
	v_and_b32_e32 v159, 0xffff0000, v206
	v_lshlrev_b32_e32 v146, 16, v207
	v_and_b32_e32 v147, 0xffff0000, v207
	v_lshlrev_b32_e32 v160, 16, v208
	v_and_b32_e32 v161, 0xffff0000, v208
	v_lshlrev_b32_e32 v148, 16, v209
	v_and_b32_e32 v149, 0xffff0000, v209
	v_pk_mul_f32 v[146:147], v[150:151], v[146:147] op_sel_hi:[0,1]
	v_pk_mul_f32 v[158:159], v[150:151], v[158:159] op_sel_hi:[0,1]
	v_pk_fma_f32 v[162:163], v[136:137], v[146:147], v[124:125]
	v_pk_mul_f32 v[146:147], v[150:151], v[160:161] op_sel_hi:[0,1]
	v_pk_mul_f32 v[148:149], v[150:151], v[148:149] op_sel_hi:[0,1]
	v_pk_fma_f32 v[158:159], v[134:135], v[158:159], v[122:123]
	v_pk_fma_f32 v[150:151], v[132:133], v[148:149], v[128:129]
	v_pk_fma_f32 v[160:161], v[130:131], v[146:147], v[126:127]
	v_cvt_pk_bf16_f32 v146, v158, v159
	v_cvt_pk_bf16_f32 v147, v162, v163
	s_nop 0
	v_cvt_pk_bf16_f32 v148, v160, v161
	v_cvt_pk_bf16_f32 v149, v150, v151
	global_store_dwordx4 v[152:153], v[146:149], off offset:256
	s_nop 1
	v_pk_fma_f32 v[146:147], v[162:163], v[162:163], v[156:157]
	v_pk_fma_f32 v[148:149], v[158:159], v[158:159], v[154:155]
	v_pk_fma_f32 v[146:147], v[150:151], v[150:151], v[146:147]
	v_pk_fma_f32 v[148:149], v[160:161], v[160:161], v[148:149]
	v_add_f32_e32 v146, v146, v147
	v_add_f32_e32 v148, v148, v149
	v_add_f32_e32 v146, v148, v146
	ds_bpermute_b32 v147, v178, v146
	ds_read_b32 v154, v174 offset:512
	s_waitcnt lgkmcnt(1)
	v_add_f32_e32 v183, v146, v147
	global_load_dwordx4 v[206:209], v251, s[74:75] offset:256
	ds_bpermute_b32 v184, v177, v183
	s_waitcnt vmcnt(10)
	v_lshlrev_b32_e32 v150, 16, v210
	v_and_b32_e32 v151, 0xffff0000, v210
	v_lshlrev_b32_e32 v146, 16, v211
	v_and_b32_e32 v147, 0xffff0000, v211
	v_lshlrev_b32_e32 v152, 16, v212
	v_and_b32_e32 v153, 0xffff0000, v212
	v_lshlrev_b32_e32 v148, 16, v213
	v_and_b32_e32 v149, 0xffff0000, v213
	s_waitcnt lgkmcnt(1)
	v_pk_mul_f32 v[146:147], v[154:155], v[146:147] op_sel_hi:[0,1]
	v_pk_mul_f32 v[150:151], v[154:155], v[150:151] op_sel_hi:[0,1]
	v_pk_fma_f32 v[156:157], v[144:145], v[146:147], v[12:13]
	v_pk_mul_f32 v[146:147], v[154:155], v[152:153] op_sel_hi:[0,1]
	v_pk_mul_f32 v[148:149], v[154:155], v[148:149] op_sel_hi:[0,1]
	v_pk_fma_f32 v[158:159], v[142:143], v[150:151], v[10:11]
	v_pk_fma_f32 v[160:161], v[140:141], v[148:149], v[8:9]
	v_pk_fma_f32 v[162:163], v[138:139], v[146:147], v[6:7]
	v_cvt_pk_bf16_f32 v146, v158, v159
	v_cvt_pk_bf16_f32 v147, v156, v157
	v_pk_mul_f32 v[156:157], v[156:157], v[156:157]
	v_cvt_pk_bf16_f32 v148, v162, v163
	v_cvt_pk_bf16_f32 v149, v160, v161
	v_add_u32_e32 v251, 0x8000, v251
	global_load_dwordx4 v[210:213], v251, s[74:75]
	v_pk_mul_f32 v[158:159], v[158:159], v[158:159]
	v_pk_fma_f32 v[156:157], v[160:161], v[160:161], v[156:157]
	v_pk_fma_f32 v[158:159], v[162:163], v[162:163], v[158:159]
	s_waitcnt vmcnt(9)
	v_lshlrev_b32_e32 v160, 16, v214
	v_and_b32_e32 v161, 0xffff0000, v214
	v_lshlrev_b32_e32 v150, 16, v215
	v_and_b32_e32 v151, 0xffff0000, v215
	v_lshlrev_b32_e32 v162, 16, v216
	v_and_b32_e32 v163, 0xffff0000, v216
	v_lshlrev_b32_e32 v152, 16, v217
	v_and_b32_e32 v153, 0xffff0000, v217
	v_pk_mul_f32 v[160:161], v[154:155], v[160:161] op_sel_hi:[0,1]
	v_pk_mul_f32 v[150:151], v[154:155], v[150:151] op_sel_hi:[0,1]
	v_pk_fma_f32 v[164:165], v[136:137], v[150:151], v[36:37]
	v_pk_fma_f32 v[160:161], v[134:135], v[160:161], v[34:35]
	v_pk_mul_f32 v[150:151], v[154:155], v[162:163] op_sel_hi:[0,1]
	v_pk_mul_f32 v[152:153], v[154:155], v[152:153] op_sel_hi:[0,1]
	v_pk_fma_f32 v[154:155], v[132:133], v[152:153], v[32:33]
	v_pk_fma_f32 v[162:163], v[130:131], v[150:151], v[30:31]
	v_pk_fma_f32 v[156:157], v[164:165], v[164:165], v[156:157]
	v_pk_fma_f32 v[158:159], v[160:161], v[160:161], v[158:159]
	v_cvt_pk_bf16_f32 v150, v160, v161
	v_cvt_pk_bf16_f32 v151, v164, v165
	v_cvt_pk_bf16_f32 v152, v162, v163
	v_cvt_pk_bf16_f32 v153, v154, v155
	v_pk_fma_f32 v[154:155], v[154:155], v[154:155], v[156:157]
	v_pk_fma_f32 v[156:157], v[162:163], v[162:163], v[158:159]
	v_add_f32_e32 v154, v154, v155
	v_add_f32_e32 v156, v156, v157
	v_add_f32_e32 v154, v156, v154
	ds_bpermute_b32 v155, v178, v154
	ds_read_b32 v162, v174 offset:576
	s_waitcnt lgkmcnt(1)
	v_add_f32_e32 v185, v154, v155
	v_add_u32_e32 v154, 0x90, v170
	v_ashrrev_i32_e32 v155, 31, v154
	v_lshlrev_b64 v[154:155], 11, v[154:155]
	v_lshl_add_u64 v[154:155], s[74:75], 0, v[154:155]
	v_lshl_add_u64 v[158:159], v[154:155], 0, v[172:173]
	global_load_dwordx4 v[214:217], v251, s[74:75] offset:256
	ds_bpermute_b32 v186, v177, v185
	s_waitcnt vmcnt(8)
	v_lshlrev_b32_e32 v160, 16, v218
	v_and_b32_e32 v161, 0xffff0000, v218
	v_lshlrev_b32_e32 v154, 16, v219
	v_and_b32_e32 v155, 0xffff0000, v219
	v_lshlrev_b32_e32 v164, 16, v220
	v_and_b32_e32 v165, 0xffff0000, v220
	v_lshlrev_b32_e32 v156, 16, v221
	v_and_b32_e32 v157, 0xffff0000, v221
	s_waitcnt lgkmcnt(1)
	v_pk_mul_f32 v[154:155], v[162:163], v[154:155] op_sel_hi:[0,1]
	v_pk_mul_f32 v[160:161], v[162:163], v[160:161] op_sel_hi:[0,1]
	v_pk_fma_f32 v[166:167], v[144:145], v[154:155], v[4:5]
	v_pk_mul_f32 v[154:155], v[162:163], v[164:165] op_sel_hi:[0,1]
	v_pk_mul_f32 v[156:157], v[162:163], v[156:157] op_sel_hi:[0,1]
	v_pk_fma_f32 v[168:169], v[142:143], v[160:161], v[2:3]
	v_pk_fma_f32 v[164:165], v[140:141], v[156:157], v[20:21]
	v_pk_fma_f32 v[188:189], v[138:139], v[154:155], v[18:19]
	v_cvt_pk_bf16_f32 v154, v168, v169
	v_cvt_pk_bf16_f32 v155, v166, v167
	v_pk_mul_f32 v[166:167], v[166:167], v[166:167]
	v_cvt_pk_bf16_f32 v156, v188, v189
	v_cvt_pk_bf16_f32 v157, v164, v165
	v_pk_mul_f32 v[168:169], v[168:169], v[168:169]
	v_pk_fma_f32 v[164:165], v[164:165], v[164:165], v[166:167]
	v_pk_fma_f32 v[166:167], v[188:189], v[188:189], v[168:169]
	s_waitcnt vmcnt(6)
	v_lshlrev_b32_e32 v168, 16, v222
	v_and_b32_e32 v169, 0xffff0000, v222
	v_lshlrev_b32_e32 v158, 16, v223
	v_and_b32_e32 v159, 0xffff0000, v223
	v_lshlrev_b32_e32 v188, 16, v224
	v_and_b32_e32 v189, 0xffff0000, v224
	v_lshlrev_b32_e32 v160, 16, v225
	v_and_b32_e32 v161, 0xffff0000, v225
	v_pk_mul_f32 v[168:169], v[162:163], v[168:169] op_sel_hi:[0,1]
	v_pk_mul_f32 v[158:159], v[162:163], v[158:159] op_sel_hi:[0,1]
	v_pk_fma_f32 v[190:191], v[136:137], v[158:159], v[44:45]
	v_pk_fma_f32 v[168:169], v[134:135], v[168:169], v[42:43]
	v_pk_mul_f32 v[158:159], v[162:163], v[188:189] op_sel_hi:[0,1]
	v_pk_mul_f32 v[160:161], v[162:163], v[160:161] op_sel_hi:[0,1]
	v_pk_fma_f32 v[162:163], v[132:133], v[160:161], v[48:49]
	v_pk_fma_f32 v[188:189], v[130:131], v[158:159], v[46:47]
	v_pk_fma_f32 v[164:165], v[190:191], v[190:191], v[164:165]
	v_pk_fma_f32 v[166:167], v[168:169], v[168:169], v[166:167]
	v_cvt_pk_bf16_f32 v158, v168, v169
	v_cvt_pk_bf16_f32 v159, v190, v191
	v_cvt_pk_bf16_f32 v160, v188, v189
	v_cvt_pk_bf16_f32 v161, v162, v163
	v_pk_fma_f32 v[162:163], v[162:163], v[162:163], v[164:165]
	v_pk_fma_f32 v[164:165], v[188:189], v[188:189], v[166:167]
	v_add_f32_e32 v162, v162, v163
	v_add_f32_e32 v164, v164, v165
	v_add_f32_e32 v162, v164, v162
	ds_bpermute_b32 v163, v178, v162
	ds_read_b32 v190, v174 offset:640
	s_waitcnt lgkmcnt(1)
	v_add_f32_e32 v187, v162, v163
	v_add_u32_e32 v162, 0xa0, v170
	v_ashrrev_i32_e32 v163, 31, v162
	v_lshlrev_b64 v[162:163], 11, v[162:163]
	v_lshl_add_u64 v[162:163], s[74:75], 0, v[162:163]
	v_lshl_add_u64 v[166:167], v[162:163], 0, v[172:173]
	ds_bpermute_b32 v188, v177, v187
	s_waitcnt vmcnt(4)
	v_lshlrev_b32_e32 v168, 16, v202
	v_and_b32_e32 v169, 0xffff0000, v202
	v_lshlrev_b32_e32 v162, 16, v203
	v_and_b32_e32 v163, 0xffff0000, v203
	v_lshlrev_b32_e32 v192, 16, v204
	v_and_b32_e32 v193, 0xffff0000, v204
	v_lshlrev_b32_e32 v164, 16, v205
	v_and_b32_e32 v165, 0xffff0000, v205
	s_waitcnt lgkmcnt(1)
	v_pk_mul_f32 v[162:163], v[190:191], v[162:163] op_sel_hi:[0,1]
	v_pk_mul_f32 v[168:169], v[190:191], v[168:169] op_sel_hi:[0,1]
	v_pk_fma_f32 v[194:195], v[144:145], v[162:163], v[16:17]
	v_pk_mul_f32 v[162:163], v[190:191], v[192:193] op_sel_hi:[0,1]
	v_pk_mul_f32 v[164:165], v[190:191], v[164:165] op_sel_hi:[0,1]
	v_pk_fma_f32 v[196:197], v[142:143], v[168:169], v[14:15]
	v_pk_fma_f32 v[192:193], v[140:141], v[164:165], v[28:29]
	v_pk_fma_f32 v[198:199], v[138:139], v[162:163], v[26:27]
	v_cvt_pk_bf16_f32 v162, v196, v197
	v_cvt_pk_bf16_f32 v163, v194, v195
	v_pk_mul_f32 v[194:195], v[194:195], v[194:195]
	v_cvt_pk_bf16_f32 v164, v198, v199
	v_cvt_pk_bf16_f32 v165, v192, v193
	v_pk_mul_f32 v[196:197], v[196:197], v[196:197]
	v_pk_fma_f32 v[192:193], v[192:193], v[192:193], v[194:195]
	v_pk_fma_f32 v[194:195], v[198:199], v[198:199], v[196:197]
	s_waitcnt vmcnt(2)
	v_lshlrev_b32_e32 v196, 16, v206
	v_and_b32_e32 v197, 0xffff0000, v206
	v_lshlrev_b32_e32 v166, 16, v207
	v_and_b32_e32 v167, 0xffff0000, v207
	v_lshlrev_b32_e32 v198, 16, v208
	v_and_b32_e32 v199, 0xffff0000, v208
	v_lshlrev_b32_e32 v168, 16, v209
	v_and_b32_e32 v169, 0xffff0000, v209
	v_pk_mul_f32 v[196:197], v[190:191], v[196:197] op_sel_hi:[0,1]
	v_pk_mul_f32 v[166:167], v[190:191], v[166:167] op_sel_hi:[0,1]
	v_pk_fma_f32 v[200:201], v[136:137], v[166:167], v[52:53]
	v_pk_fma_f32 v[196:197], v[134:135], v[196:197], v[50:51]
	v_pk_mul_f32 v[166:167], v[190:191], v[198:199] op_sel_hi:[0,1]
	v_pk_mul_f32 v[168:169], v[190:191], v[168:169] op_sel_hi:[0,1]
	v_pk_fma_f32 v[190:191], v[132:133], v[168:169], v[56:57]
	v_pk_fma_f32 v[198:199], v[130:131], v[166:167], v[54:55]
	v_pk_fma_f32 v[192:193], v[200:201], v[200:201], v[192:193]
	v_pk_fma_f32 v[194:195], v[196:197], v[196:197], v[194:195]
	v_cvt_pk_bf16_f32 v166, v196, v197
	v_cvt_pk_bf16_f32 v167, v200, v201
	v_cvt_pk_bf16_f32 v168, v198, v199
	v_cvt_pk_bf16_f32 v169, v190, v191
	v_pk_fma_f32 v[190:191], v[190:191], v[190:191], v[192:193]
	v_pk_fma_f32 v[192:193], v[198:199], v[198:199], v[194:195]
	ds_read_b32 v174, v174 offset:704
	v_add_f32_e32 v189, v192, v193
	v_add_u32_e32 v192, 0xb0, v170
	v_ashrrev_i32_e32 v193, 31, v192
	v_lshlrev_b64 v[192:193], 11, v[192:193]
	v_lshl_add_u64 v[192:193], s[74:75], 0, v[192:193]
	v_lshl_add_u64 v[172:173], v[192:193], 0, v[172:173]
	v_add_f32_e32 v190, v190, v191
	v_add_f32_e32 v189, v189, v190
	ds_bpermute_b32 v190, v178, v189
	s_waitcnt lgkmcnt(0)
	v_add_f32_e32 v189, v189, v190
	ds_bpermute_b32 v190, v177, v189
	s_waitcnt vmcnt(1)
	v_lshlrev_b32_e32 v196, 16, v210
	v_and_b32_e32 v197, 0xffff0000, v210
	v_lshlrev_b32_e32 v192, 16, v211
	v_and_b32_e32 v193, 0xffff0000, v211
	v_lshlrev_b32_e32 v198, 16, v212
	v_and_b32_e32 v199, 0xffff0000, v212
	v_lshlrev_b32_e32 v194, 16, v213
	v_and_b32_e32 v195, 0xffff0000, v213
	v_pk_mul_f32 v[192:193], v[174:175], v[192:193] op_sel_hi:[0,1]
	v_pk_mul_f32 v[196:197], v[174:175], v[196:197] op_sel_hi:[0,1]
	v_pk_fma_f32 v[144:145], v[144:145], v[192:193], v[24:25]
	v_pk_mul_f32 v[192:193], v[174:175], v[198:199] op_sel_hi:[0,1]
	v_pk_mul_f32 v[194:195], v[174:175], v[194:195] op_sel_hi:[0,1]
	v_pk_fma_f32 v[142:143], v[142:143], v[196:197], v[22:23]
	v_pk_fma_f32 v[196:197], v[140:141], v[194:195], v[40:41]
	v_pk_fma_f32 v[198:199], v[138:139], v[192:193], v[38:39]
	v_cvt_pk_bf16_f32 v138, v142, v143
	v_cvt_pk_bf16_f32 v139, v144, v145
	v_pk_mul_f32 v[144:145], v[144:145], v[144:145]
	v_cvt_pk_bf16_f32 v140, v198, v199
	v_cvt_pk_bf16_f32 v141, v196, v197
	v_pk_mul_f32 v[142:143], v[142:143], v[142:143]
	v_pk_fma_f32 v[144:145], v[196:197], v[196:197], v[144:145]
	v_pk_fma_f32 v[142:143], v[198:199], v[198:199], v[142:143]
	s_waitcnt vmcnt(0)
	v_lshlrev_b32_e32 v172, 16, v214
	v_and_b32_e32 v173, 0xffff0000, v214
	v_lshlrev_b32_e32 v192, 16, v215
	v_and_b32_e32 v193, 0xffff0000, v215
	v_lshlrev_b32_e32 v196, 16, v216
	v_and_b32_e32 v197, 0xffff0000, v216
	v_lshlrev_b32_e32 v194, 16, v217
	v_and_b32_e32 v195, 0xffff0000, v217
	v_pk_mul_f32 v[172:173], v[174:175], v[172:173] op_sel_hi:[0,1]
	v_pk_mul_f32 v[192:193], v[174:175], v[192:193] op_sel_hi:[0,1]
	v_pk_fma_f32 v[136:137], v[136:137], v[192:193], v[60:61]
	v_pk_fma_f32 v[134:135], v[134:135], v[172:173], v[58:59]
	v_pk_mul_f32 v[172:173], v[174:175], v[196:197] op_sel_hi:[0,1]
	v_pk_mul_f32 v[192:193], v[174:175], v[194:195] op_sel_hi:[0,1]
	v_pk_fma_f32 v[192:193], v[132:133], v[192:193], v[64:65]
	v_pk_fma_f32 v[172:173], v[130:131], v[172:173], v[62:63]
	v_cvt_pk_bf16_f32 v130, v134, v135
	v_cvt_pk_bf16_f32 v131, v136, v137
	v_pk_fma_f32 v[136:137], v[136:137], v[136:137], v[144:145]
	v_pk_fma_f32 v[134:135], v[134:135], v[134:135], v[142:143]
	v_pk_fma_f32 v[136:137], v[192:193], v[192:193], v[136:137]
	v_pk_fma_f32 v[134:135], v[172:173], v[172:173], v[134:135]
	v_cvt_pk_bf16_f32 v132, v172, v173
	v_cvt_pk_bf16_f32 v133, v192, v193
	s_nop 0
	v_add_f32_e32 v134, v134, v135
	v_add_f32_e32 v135, v136, v137
	v_add_f32_e32 v134, v134, v135
	ds_bpermute_b32 v135, v178, v134
	s_waitcnt lgkmcnt(0)
	v_add_f32_e32 v134, v134, v135
	ds_bpermute_b32 v135, v177, v134
	s_and_saveexec_b64 s[0:1], vcc
	s_xor_b64 s[0:1], exec, s[0:1]
	s_cbranch_execz .LBB0_862
	v_cmp_lt_i32_e32 vcc, 1, v175
	s_and_saveexec_b64 s[18:19], vcc
	s_xor_b64 s[18:19], exec, s[18:19]
	s_cbranch_execz .LBB0_849
	v_cmp_eq_u32_e32 vcc, 2, v175
	s_mov_b64 s[4:5], -1
	s_and_saveexec_b64 s[20:21], vcc
	v_add_f32_e32 v142, v185, v186
	s_xor_b64 s[4:5], exec, -1
	s_or_b64 exec, exec, s[20:21]
	s_and_b64 s[4:5], s[4:5], exec

.LBB0_1254:
	s_add_i32 s98, s0, 0x100080
	s_mov_b32 s8, s70
	v_mov_b32_e32 v0, v235
	v_mov_b32_e32 v172, v236
	s_lshl_b32 s0, s40, 8
	s_add_i32 s0, s0, s59
	s_mov_b64 s[4:5], 0
	v_add_u32_e32 v162, s0, v0
	s_lshl_b32 s0, s41, 8
	s_or_b32 s0, s0, s60
	v_ashrrev_i32_e32 v163, 31, v162
	v_lshl_add_u32 v0, v172, 3, s0
	v_lshlrev_b64 v[130:131], 11, v[162:163]
	v_ashrrev_i32_e32 v1, 31, v0
	v_lshl_add_u64 v[130:131], s[74:75], 0, v[130:131]
	v_lshl_add_u64 v[154:155], v[0:1], 1, v[130:131]
	v_lshlrev_b32_e32 v192, 11, v162
	v_lshl_add_u32 v192, v0, 1, v192
	global_load_dwordx4 v[194:197], v192, s[74:75]
	global_load_dwordx4 v[198:201], v192, s[74:75] offset:256
	v_add_u32_e32 v192, 0x8000, v192
	global_load_dwordx4 v[202:205], v192, s[74:75]
	global_load_dwordx4 v[206:209], v192, s[74:75] offset:256
	v_add_u32_e32 v192, 0x8000, v192
	global_load_dwordx4 v[210:213], v192, s[74:75]
	global_load_dwordx4 v[214:217], v192, s[74:75] offset:256
	v_add_u32_e32 v192, 0x8000, v192
	global_load_dwordx4 v[218:221], v192, s[74:75]
	global_load_dwordx4 v[222:225], v192, s[74:75] offset:256
	s_mov_b32 m0, s61
	s_nop 0
	buffer_load_dwordx4 v230, s[8:11], s98 offen lds
	s_mov_b32 m0, s64
	s_nop 0
	buffer_load_dwordx4 v233, s[8:11], s98 offen lds
	s_mov_b64 s[0:1], 0x40000
	v_lshl_add_u64 v[0:1], v[154:155], 0, s[0:1]
	s_mov_b64 s[0:1], 0x8000
	s_waitcnt vmcnt(9)
	v_lshlrev_b32_e32 v134, 16, v194
	v_and_b32_e32 v135, 0xffff0000, v194
	v_lshlrev_b32_e32 v130, 16, v195
	v_and_b32_e32 v131, 0xffff0000, v195
	v_lshlrev_b32_e32 v136, 16, v196
	v_and_b32_e32 v137, 0xffff0000, v196
	v_lshlrev_b32_e32 v132, 16, v197
	v_and_b32_e32 v133, 0xffff0000, v197
	v_pk_add_f32 v[138:139], v[76:77], v[130:131]
	v_pk_add_f32 v[134:135], v[74:75], v[134:135]
	v_pk_add_f32 v[140:141], v[72:73], v[132:133]
	v_pk_add_f32 v[136:137], v[70:71], v[136:137]
	v_cvt_pk_bf16_f32 v130, v134, v135
	v_cvt_pk_bf16_f32 v131, v138, v139
	v_pk_mul_f32 v[134:135], v[134:135], v[134:135]
	v_cvt_pk_bf16_f32 v132, v136, v137
	v_cvt_pk_bf16_f32 v133, v140, v141
	global_store_dwordx4 v[154:155], v[130:133], off
	v_add_u32_e32 v192, 0x28000, v192
	global_load_dwordx4 v[194:197], v192, s[74:75]
	v_pk_mul_f32 v[138:139], v[138:139], v[138:139]
	v_pk_fma_f32 v[134:135], v[136:137], v[136:137], v[134:135]
	v_pk_fma_f32 v[138:139], v[140:141], v[140:141], v[138:139]
	s_waitcnt vmcnt(10)
	v_lshlrev_b32_e32 v136, 16, v198
	v_and_b32_e32 v137, 0xffff0000, v198
	v_lshlrev_b32_e32 v130, 16, v199
	v_and_b32_e32 v131, 0xffff0000, v199
	v_lshlrev_b32_e32 v140, 16, v200
	v_and_b32_e32 v141, 0xffff0000, v200
	v_lshlrev_b32_e32 v132, 16, v201
	v_and_b32_e32 v133, 0xffff0000, v201
	v_pk_add_f32 v[142:143], v[100:101], v[130:131]
	v_pk_add_f32 v[136:137], v[98:99], v[136:137]
	v_pk_add_f32 v[144:145], v[96:97], v[132:133]
	v_pk_add_f32 v[140:141], v[94:95], v[140:141]
	v_cvt_pk_bf16_f32 v130, v136, v137
	v_cvt_pk_bf16_f32 v131, v142, v143
	s_nop 0
	v_cvt_pk_bf16_f32 v132, v140, v141
	v_cvt_pk_bf16_f32 v133, v144, v145
	global_store_dwordx4 v[154:155], v[130:133], off offset:256
	s_nop 1
	v_pk_fma_f32 v[130:131], v[136:137], v[136:137], v[134:135]
	v_pk_fma_f32 v[132:133], v[142:143], v[142:143], v[138:139]
	v_pk_fma_f32 v[130:131], v[140:141], v[140:141], v[130:131]
	v_pk_fma_f32 v[132:133], v[144:145], v[144:145], v[132:133]
	s_nop 0
	v_pk_mov_b32 v[134:135], v[130:131], v[132:133] op_sel:[1,0]
	v_mov_b32_e32 v131, v133
	v_pk_add_f32 v[130:131], v[134:135], v[130:131]
	v_and_b32_e32 v132, 64, v249
	v_add_f32_e32 v130, v130, v131
	v_xor_b32_e32 v131, 16, v249
	v_add_u32_e32 v132, 64, v132
	v_cmp_lt_i32_e32 vcc, v131, v132
	s_nop 1
	v_cndmask_b32_e32 v131, v249, v131, vcc
	v_lshlrev_b32_e32 v175, 2, v131
	ds_bpermute_b32 v131, v175, v130
	s_waitcnt lgkmcnt(0)
	v_add_f32_e32 v163, v130, v131
	v_xor_b32_e32 v130, 32, v249
	v_cmp_lt_i32_e32 vcc, v130, v132
	s_nop 1
	v_cndmask_b32_e32 v130, v249, v130, vcc
	v_lshlrev_b32_e32 v174, 2, v130
	v_lshl_add_u64 v[130:131], v[154:155], 0, s[0:1]
	s_mov_b32 s0, 0x8000
	v_add_co_u32_e32 v136, vcc, s0, v154
	s_mov_b32 s0, 0x10000
	s_nop 0
	v_addc_co_u32_e32 v137, vcc, 0, v155, vcc
	global_load_dwordx4 v[198:201], v192, s[74:75] offset:256
	ds_bpermute_b32 v173, v174, v163
	s_waitcnt vmcnt(11)
	v_lshlrev_b32_e32 v138, 16, v202
	v_and_b32_e32 v139, 0xffff0000, v202
	v_lshlrev_b32_e32 v132, 16, v203
	v_and_b32_e32 v133, 0xffff0000, v203
	v_lshlrev_b32_e32 v140, 16, v204
	v_and_b32_e32 v141, 0xffff0000, v204
	v_lshlrev_b32_e32 v134, 16, v205
	v_and_b32_e32 v135, 0xffff0000, v205
	v_pk_add_f32 v[142:143], v[68:69], v[132:133]
	v_pk_add_f32 v[138:139], v[66:67], v[138:139]
	v_pk_add_f32 v[144:145], v[84:85], v[134:135]
	v_pk_add_f32 v[140:141], v[82:83], v[140:141]
	v_cvt_pk_bf16_f32 v132, v138, v139
	v_cvt_pk_bf16_f32 v133, v142, v143
	s_nop 0
	v_cvt_pk_bf16_f32 v134, v140, v141
	v_cvt_pk_bf16_f32 v135, v144, v145
	global_store_dwordx4 v[136:137], v[132:135], off
	v_add_u32_e32 v192, 0x8000, v192
	global_load_dwordx4 v[202:205], v192, s[74:75]
	v_pk_mul_f32 v[136:137], v[138:139], v[138:139]
	v_pk_mul_f32 v[138:139], v[142:143], v[142:143]
	v_pk_fma_f32 v[136:137], v[140:141], v[140:141], v[136:137]
	v_pk_fma_f32 v[138:139], v[144:145], v[144:145], v[138:139]
	s_waitcnt vmcnt(12)
	v_lshlrev_b32_e32 v140, 16, v206
	v_and_b32_e32 v141, 0xffff0000, v206
	v_lshlrev_b32_e32 v132, 16, v207
	v_and_b32_e32 v133, 0xffff0000, v207
	v_lshlrev_b32_e32 v142, 16, v208
	v_and_b32_e32 v143, 0xffff0000, v208
	v_lshlrev_b32_e32 v134, 16, v209
	v_and_b32_e32 v135, 0xffff0000, v209
	v_pk_add_f32 v[144:145], v[108:109], v[132:133]
	v_pk_add_f32 v[140:141], v[106:107], v[140:141]
	v_pk_add_f32 v[146:147], v[112:113], v[134:135]
	v_cvt_pk_bf16_f32 v132, v140, v141
	v_cvt_pk_bf16_f32 v133, v144, v145
	v_pk_add_f32 v[142:143], v[110:111], v[142:143]
	s_nop 0
	v_cvt_pk_bf16_f32 v134, v142, v143
	v_cvt_pk_bf16_f32 v135, v146, v147
	global_store_dwordx4 v[130:131], v[132:135], off offset:256
	v_pk_fma_f32 v[130:131], v[140:141], v[140:141], v[136:137]
	v_add_co_u32_e32 v136, vcc, s0, v154
	v_pk_fma_f32 v[132:133], v[144:145], v[144:145], v[138:139]
	v_pk_fma_f32 v[130:131], v[142:143], v[142:143], v[130:131]
	v_pk_fma_f32 v[132:133], v[146:147], v[146:147], v[132:133]
	v_addc_co_u32_e32 v137, vcc, 0, v155, vcc
	v_add_f32_e32 v130, v130, v131
	v_add_f32_e32 v131, v132, v133
	global_load_dwordx4 v[206:209], v192, s[74:75] offset:256
	v_add_f32_e32 v130, v130, v131
	ds_bpermute_b32 v131, v175, v130
	s_mov_b32 s0, 0x18000
	s_waitcnt lgkmcnt(0)
	v_add_f32_e32 v176, v130, v131
	v_lshl_add_u64 v[130:131], v[154:155], 0, s[20:21]
	ds_bpermute_b32 v177, v174, v176
	s_waitcnt vmcnt(13)
	v_lshlrev_b32_e32 v138, 16, v210
	v_and_b32_e32 v139, 0xffff0000, v210
	v_lshlrev_b32_e32 v132, 16, v211
	v_and_b32_e32 v133, 0xffff0000, v211
	v_lshlrev_b32_e32 v140, 16, v212
	v_and_b32_e32 v141, 0xffff0000, v212
	v_lshlrev_b32_e32 v134, 16, v213
	v_and_b32_e32 v135, 0xffff0000, v213
	v_pk_add_f32 v[142:143], v[80:81], v[132:133]
	v_pk_add_f32 v[138:139], v[78:79], v[138:139]
	v_pk_add_f32 v[144:145], v[92:93], v[134:135]
	v_pk_add_f32 v[140:141], v[90:91], v[140:141]
	v_cvt_pk_bf16_f32 v132, v138, v139
	v_cvt_pk_bf16_f32 v133, v142, v143
	s_nop 0
	v_cvt_pk_bf16_f32 v134, v140, v141
	v_cvt_pk_bf16_f32 v135, v144, v145
	global_store_dwordx4 v[136:137], v[132:135], off
	v_add_u32_e32 v192, 0x8000, v192
	global_load_dwordx4 v[210:213], v192, s[74:75]
	v_pk_mul_f32 v[136:137], v[138:139], v[138:139]
	v_pk_mul_f32 v[138:139], v[142:143], v[142:143]
	v_pk_fma_f32 v[136:137], v[140:141], v[140:141], v[136:137]
	v_pk_fma_f32 v[138:139], v[144:145], v[144:145], v[138:139]
	s_waitcnt vmcnt(14)
	v_lshlrev_b32_e32 v140, 16, v214
	v_and_b32_e32 v141, 0xffff0000, v214
	v_lshlrev_b32_e32 v132, 16, v215
	v_and_b32_e32 v133, 0xffff0000, v215
	v_lshlrev_b32_e32 v142, 16, v216
	v_and_b32_e32 v143, 0xffff0000, v216
	v_lshlrev_b32_e32 v134, 16, v217
	v_and_b32_e32 v135, 0xffff0000, v217
	v_pk_add_f32 v[144:145], v[116:117], v[132:133]
	v_pk_add_f32 v[140:141], v[114:115], v[140:141]
	v_pk_add_f32 v[146:147], v[120:121], v[134:135]
	v_cvt_pk_bf16_f32 v132, v140, v141
	v_cvt_pk_bf16_f32 v133, v144, v145
	v_pk_add_f32 v[142:143], v[118:119], v[142:143]
	s_nop 0
	v_cvt_pk_bf16_f32 v134, v142, v143
	v_cvt_pk_bf16_f32 v135, v146, v147
	global_store_dwordx4 v[130:131], v[132:135], off offset:256
	v_pk_fma_f32 v[130:131], v[140:141], v[140:141], v[136:137]
	v_add_co_u32_e32 v136, vcc, s0, v154
	v_pk_fma_f32 v[132:133], v[144:145], v[144:145], v[138:139]
	v_pk_fma_f32 v[130:131], v[142:143], v[142:143], v[130:131]
	v_pk_fma_f32 v[132:133], v[146:147], v[146:147], v[132:133]
	v_addc_co_u32_e32 v137, vcc, 0, v155, vcc
	v_add_f32_e32 v130, v130, v131
	v_add_f32_e32 v131, v132, v133
	global_load_dwordx4 v[214:217], v192, s[74:75] offset:256
	v_add_f32_e32 v130, v130, v131
	ds_bpermute_b32 v131, v175, v130
	s_waitcnt lgkmcnt(0)
	v_add_f32_e32 v178, v130, v131
	v_lshl_add_u64 v[130:131], v[154:155], 0, s[22:23]
	ds_bpermute_b32 v179, v174, v178
	s_waitcnt vmcnt(15)
	v_lshlrev_b32_e32 v138, 16, v218
	v_and_b32_e32 v139, 0xffff0000, v218
	v_lshlrev_b32_e32 v132, 16, v219
	v_and_b32_e32 v133, 0xffff0000, v219
	v_lshlrev_b32_e32 v140, 16, v220
	v_and_b32_e32 v141, 0xffff0000, v220
	v_lshlrev_b32_e32 v134, 16, v221
	v_and_b32_e32 v135, 0xffff0000, v221
	v_pk_add_f32 v[142:143], v[88:89], v[132:133]
	v_pk_add_f32 v[138:139], v[86:87], v[138:139]
	v_pk_add_f32 v[144:145], v[104:105], v[134:135]
	v_pk_add_f32 v[140:141], v[102:103], v[140:141]
	v_cvt_pk_bf16_f32 v132, v138, v139
	v_cvt_pk_bf16_f32 v133, v142, v143
	s_nop 0
	v_cvt_pk_bf16_f32 v134, v140, v141
	v_cvt_pk_bf16_f32 v135, v144, v145
	global_store_dwordx4 v[136:137], v[132:135], off
	v_add_u32_e32 v192, 0x8000, v192
	global_load_dwordx4 v[218:221], v192, s[74:75]
	v_pk_mul_f32 v[136:137], v[138:139], v[138:139]
	v_pk_mul_f32 v[138:139], v[142:143], v[142:143]
	v_pk_fma_f32 v[136:137], v[140:141], v[140:141], v[136:137]
	v_pk_fma_f32 v[138:139], v[144:145], v[144:145], v[138:139]
	s_waitcnt vmcnt(16)
	v_lshlrev_b32_e32 v140, 16, v222
	v_and_b32_e32 v141, 0xffff0000, v222
	v_lshlrev_b32_e32 v132, 16, v223
	v_and_b32_e32 v133, 0xffff0000, v223
	v_lshlrev_b32_e32 v142, 16, v224
	v_and_b32_e32 v143, 0xffff0000, v224
	v_lshlrev_b32_e32 v134, 16, v225
	v_and_b32_e32 v135, 0xffff0000, v225
	v_pk_add_f32 v[144:145], v[124:125], v[132:133]
	v_pk_add_f32 v[140:141], v[122:123], v[140:141]
	v_pk_add_f32 v[146:147], v[128:129], v[134:135]
	v_cvt_pk_bf16_f32 v132, v140, v141
	v_cvt_pk_bf16_f32 v133, v144, v145
	v_pk_add_f32 v[142:143], v[126:127], v[142:143]
	s_nop 0
	v_cvt_pk_bf16_f32 v134, v142, v143
	v_cvt_pk_bf16_f32 v135, v146, v147
	global_store_dwordx4 v[130:131], v[132:135], off offset:256
	v_pk_fma_f32 v[130:131], v[140:141], v[140:141], v[136:137]
	s_nop 0
	v_pk_fma_f32 v[132:133], v[144:145], v[144:145], v[138:139]
	v_pk_fma_f32 v[130:131], v[142:143], v[142:143], v[130:131]
	v_pk_fma_f32 v[132:133], v[146:147], v[146:147], v[132:133]
	v_add_f32_e32 v130, v130, v131
	v_add_f32_e32 v131, v132, v133
	v_add_f32_e32 v130, v130, v131
	ds_bpermute_b32 v131, v175, v130
	s_waitcnt lgkmcnt(0)
	v_add_f32_e32 v180, v130, v131
	v_add_co_u32_e32 v130, vcc, s76, v154
	ds_bpermute_b32 v181, v174, v180
	s_nop 0
	v_addc_co_u32_e32 v131, vcc, 0, v155, vcc
	global_load_dwordx4 v[222:225], v192, s[74:75] offset:256
	s_waitcnt vmcnt(14)
	v_lshlrev_b32_e32 v134, 16, v194
	v_and_b32_e32 v135, 0xffff0000, v194
	v_lshlrev_b32_e32 v130, 16, v195
	v_and_b32_e32 v131, 0xffff0000, v195
	v_lshlrev_b32_e32 v136, 16, v196
	v_and_b32_e32 v137, 0xffff0000, v196
	v_lshlrev_b32_e32 v132, 16, v197
	v_and_b32_e32 v133, 0xffff0000, v197
	v_pk_add_f32 v[138:139], v[12:13], v[130:131]
	v_pk_add_f32 v[140:141], v[10:11], v[134:135]
	v_pk_add_f32 v[142:143], v[8:9], v[132:133]
	v_pk_add_f32 v[144:145], v[6:7], v[136:137]
	v_cvt_pk_bf16_f32 v130, v140, v141
	v_cvt_pk_bf16_f32 v131, v138, v139
	v_pk_mul_f32 v[138:139], v[138:139], v[138:139]
	v_cvt_pk_bf16_f32 v132, v144, v145
	v_cvt_pk_bf16_f32 v133, v142, v143
	v_pk_mul_f32 v[140:141], v[140:141], v[140:141]
	v_pk_fma_f32 v[138:139], v[142:143], v[142:143], v[138:139]
	v_pk_fma_f32 v[140:141], v[144:145], v[144:145], v[140:141]
	s_waitcnt vmcnt(12)
	v_lshlrev_b32_e32 v142, 16, v198
	v_and_b32_e32 v143, 0xffff0000, v198
	v_lshlrev_b32_e32 v134, 16, v199
	v_and_b32_e32 v135, 0xffff0000, v199
	v_lshlrev_b32_e32 v144, 16, v200
	v_and_b32_e32 v145, 0xffff0000, v200
	v_lshlrev_b32_e32 v136, 16, v201
	v_and_b32_e32 v137, 0xffff0000, v201
	v_pk_add_f32 v[146:147], v[36:37], v[134:135]
	v_pk_add_f32 v[142:143], v[34:35], v[142:143]
	v_pk_add_f32 v[148:149], v[32:33], v[136:137]
	v_pk_add_f32 v[144:145], v[30:31], v[144:145]
	v_pk_fma_f32 v[140:141], v[142:143], v[142:143], v[140:141]
	v_pk_fma_f32 v[138:139], v[146:147], v[146:147], v[138:139]
	v_pk_fma_f32 v[140:141], v[144:145], v[144:145], v[140:141]
	v_pk_fma_f32 v[138:139], v[148:149], v[148:149], v[138:139]
	v_add_f32_e32 v140, v140, v141
	v_add_f32_e32 v138, v138, v139
	v_add_f32_e32 v138, v140, v138
	ds_bpermute_b32 v139, v175, v138
	v_cvt_pk_bf16_f32 v134, v142, v143
	v_cvt_pk_bf16_f32 v135, v146, v147
	v_cvt_pk_bf16_f32 v136, v144, v145
	v_cvt_pk_bf16_f32 v137, v148, v149
	s_waitcnt lgkmcnt(0)
	v_add_f32_e32 v182, v138, v139
	v_add_co_u32_e32 v138, vcc, s77, v154
	v_lshl_add_u64 v[142:143], v[154:155], 0, s[24:25]
	s_nop 0
	v_addc_co_u32_e32 v139, vcc, 0, v155, vcc
	ds_bpermute_b32 v183, v174, v182
	s_waitcnt vmcnt(10)
	v_lshlrev_b32_e32 v144, 16, v202
	v_and_b32_e32 v145, 0xffff0000, v202
	v_lshlrev_b32_e32 v138, 16, v203
	v_and_b32_e32 v139, 0xffff0000, v203
	v_lshlrev_b32_e32 v146, 16, v204
	v_and_b32_e32 v147, 0xffff0000, v204
	v_lshlrev_b32_e32 v140, 16, v205
	v_and_b32_e32 v141, 0xffff0000, v205
	v_pk_add_f32 v[148:149], v[4:5], v[138:139]
	v_pk_add_f32 v[150:151], v[2:3], v[144:145]
	v_pk_add_f32 v[152:153], v[20:21], v[140:141]
	v_pk_add_f32 v[146:147], v[18:19], v[146:147]
	v_cvt_pk_bf16_f32 v138, v150, v151
	v_cvt_pk_bf16_f32 v139, v148, v149
	v_pk_mul_f32 v[150:151], v[150:151], v[150:151]
	v_cvt_pk_bf16_f32 v140, v146, v147
	v_cvt_pk_bf16_f32 v141, v152, v153
	v_pk_mul_f32 v[148:149], v[148:149], v[148:149]
	v_pk_fma_f32 v[146:147], v[146:147], v[146:147], v[150:151]
	v_pk_fma_f32 v[148:149], v[152:153], v[152:153], v[148:149]
	s_waitcnt vmcnt(8)
	v_lshlrev_b32_e32 v150, 16, v206
	v_and_b32_e32 v151, 0xffff0000, v206
	v_lshlrev_b32_e32 v142, 16, v207
	v_and_b32_e32 v143, 0xffff0000, v207
	v_lshlrev_b32_e32 v152, 16, v208
	v_and_b32_e32 v153, 0xffff0000, v208
	v_lshlrev_b32_e32 v144, 16, v209
	v_and_b32_e32 v145, 0xffff0000, v209
	v_pk_add_f32 v[156:157], v[44:45], v[142:143]
	v_pk_add_f32 v[150:151], v[42:43], v[150:151]
	v_pk_add_f32 v[158:159], v[48:49], v[144:145]
	v_pk_add_f32 v[152:153], v[46:47], v[152:153]
	v_pk_fma_f32 v[146:147], v[150:151], v[150:151], v[146:147]
	v_pk_fma_f32 v[148:149], v[156:157], v[156:157], v[148:149]
	v_pk_fma_f32 v[146:147], v[152:153], v[152:153], v[146:147]
	v_pk_fma_f32 v[148:149], v[158:159], v[158:159], v[148:149]
	v_add_f32_e32 v146, v146, v147
	v_add_f32_e32 v147, v148, v149
	v_add_f32_e32 v146, v146, v147
	ds_bpermute_b32 v147, v175, v146
	v_cvt_pk_bf16_f32 v142, v150, v151
	v_cvt_pk_bf16_f32 v143, v156, v157
	v_cvt_pk_bf16_f32 v144, v152, v153
	v_cvt_pk_bf16_f32 v145, v158, v159
	s_waitcnt lgkmcnt(0)
	v_add_f32_e32 v184, v146, v147
	v_add_co_u32_e32 v146, vcc, s78, v154
	v_lshl_add_u64 v[150:151], v[154:155], 0, s[26:27]
	s_nop 0
	v_addc_co_u32_e32 v147, vcc, 0, v155, vcc
	ds_bpermute_b32 v185, v174, v184
	s_waitcnt vmcnt(6)
	v_lshlrev_b32_e32 v152, 16, v210
	v_and_b32_e32 v153, 0xffff0000, v210
	v_lshlrev_b32_e32 v146, 16, v211
	v_and_b32_e32 v147, 0xffff0000, v211
	v_lshlrev_b32_e32 v156, 16, v212
	v_and_b32_e32 v157, 0xffff0000, v212
	v_lshlrev_b32_e32 v148, 16, v213
	v_and_b32_e32 v149, 0xffff0000, v213
	v_pk_add_f32 v[158:159], v[16:17], v[146:147]
	v_pk_add_f32 v[160:161], v[14:15], v[152:153]
	v_pk_add_f32 v[164:165], v[28:29], v[148:149]
	v_pk_add_f32 v[156:157], v[26:27], v[156:157]
	v_cvt_pk_bf16_f32 v146, v160, v161
	v_cvt_pk_bf16_f32 v147, v158, v159
	v_pk_mul_f32 v[160:161], v[160:161], v[160:161]
	v_cvt_pk_bf16_f32 v148, v156, v157
	v_cvt_pk_bf16_f32 v149, v164, v165
	v_pk_mul_f32 v[158:159], v[158:159], v[158:159]
	v_pk_fma_f32 v[156:157], v[156:157], v[156:157], v[160:161]
	v_pk_fma_f32 v[158:159], v[164:165], v[164:165], v[158:159]
	s_waitcnt vmcnt(4)
	v_lshlrev_b32_e32 v160, 16, v214
	v_and_b32_e32 v161, 0xffff0000, v214
	v_lshlrev_b32_e32 v150, 16, v215
	v_and_b32_e32 v151, 0xffff0000, v215
	v_lshlrev_b32_e32 v164, 16, v216
	v_and_b32_e32 v165, 0xffff0000, v216
	v_lshlrev_b32_e32 v152, 16, v217
	v_and_b32_e32 v153, 0xffff0000, v217
	v_pk_add_f32 v[166:167], v[52:53], v[150:151]
	v_pk_add_f32 v[160:161], v[50:51], v[160:161]
	v_pk_add_f32 v[168:169], v[56:57], v[152:153]
	v_pk_add_f32 v[164:165], v[54:55], v[164:165]
	v_pk_fma_f32 v[156:157], v[160:161], v[160:161], v[156:157]
	v_pk_fma_f32 v[158:159], v[166:167], v[166:167], v[158:159]
	v_pk_fma_f32 v[156:157], v[164:165], v[164:165], v[156:157]
	v_pk_fma_f32 v[158:159], v[168:169], v[168:169], v[158:159]
	v_add_f32_e32 v156, v156, v157
	v_add_f32_e32 v157, v158, v159
	v_add_f32_e32 v156, v156, v157
	ds_bpermute_b32 v157, v175, v156
	v_lshl_add_u64 v[158:159], v[154:155], 0, s[28:29]
	v_add_co_u32_e32 v154, vcc, s79, v154
	v_cvt_pk_bf16_f32 v150, v160, v161
	v_cvt_pk_bf16_f32 v151, v166, v167
	v_cvt_pk_bf16_f32 v152, v164, v165
	v_cvt_pk_bf16_f32 v153, v168, v169
	s_nop 1
	v_addc_co_u32_e32 v155, vcc, 0, v155, vcc
	s_waitcnt lgkmcnt(0)
	v_add_f32_e32 v186, v156, v157
	ds_bpermute_b32 v187, v174, v186
	v_cmp_lt_i32_e32 vcc, 0, v172
	s_waitcnt vmcnt(2)
	v_lshlrev_b32_e32 v160, 16, v218
	v_and_b32_e32 v161, 0xffff0000, v218
	v_lshlrev_b32_e32 v154, 16, v219
	v_and_b32_e32 v155, 0xffff0000, v219
	v_lshlrev_b32_e32 v170, 16, v220
	v_and_b32_e32 v171, 0xffff0000, v220
	v_lshlrev_b32_e32 v156, 16, v221
	v_and_b32_e32 v157, 0xffff0000, v221
	v_pk_add_f32 v[164:165], v[24:25], v[154:155]
	v_pk_add_f32 v[166:167], v[22:23], v[160:161]
	v_pk_add_f32 v[168:169], v[40:41], v[156:157]
	v_pk_add_f32 v[170:171], v[38:39], v[170:171]
	v_cvt_pk_bf16_f32 v154, v166, v167
	v_cvt_pk_bf16_f32 v155, v164, v165
	v_pk_mul_f32 v[164:165], v[164:165], v[164:165]
	v_cvt_pk_bf16_f32 v156, v170, v171
	v_cvt_pk_bf16_f32 v157, v168, v169
	v_pk_mul_f32 v[166:167], v[166:167], v[166:167]
	v_pk_fma_f32 v[164:165], v[168:169], v[168:169], v[164:165]
	v_pk_fma_f32 v[166:167], v[170:171], v[170:171], v[166:167]
	s_waitcnt vmcnt(0)
	v_lshlrev_b32_e32 v168, 16, v222
	v_and_b32_e32 v169, 0xffff0000, v222
	v_lshlrev_b32_e32 v158, 16, v223
	v_and_b32_e32 v159, 0xffff0000, v223
	v_lshlrev_b32_e32 v170, 16, v224
	v_and_b32_e32 v171, 0xffff0000, v224
	v_lshlrev_b32_e32 v160, 16, v225
	v_and_b32_e32 v161, 0xffff0000, v225
	v_pk_add_f32 v[188:189], v[60:61], v[158:159]
	v_pk_add_f32 v[168:169], v[58:59], v[168:169]
	v_pk_add_f32 v[190:191], v[64:65], v[160:161]
	v_pk_add_f32 v[170:171], v[62:63], v[170:171]
	v_pk_fma_f32 v[166:167], v[168:169], v[168:169], v[166:167]
	v_pk_fma_f32 v[164:165], v[188:189], v[188:189], v[164:165]
	v_pk_fma_f32 v[166:167], v[170:171], v[170:171], v[166:167]
	v_pk_fma_f32 v[164:165], v[190:191], v[190:191], v[164:165]
	v_add_f32_e32 v166, v166, v167
	v_add_f32_e32 v164, v164, v165
	v_add_f32_e32 v164, v166, v164
	ds_bpermute_b32 v165, v175, v164
	v_cvt_pk_bf16_f32 v158, v168, v169
	v_cvt_pk_bf16_f32 v159, v188, v189
	v_cvt_pk_bf16_f32 v160, v170, v171
	v_cvt_pk_bf16_f32 v161, v190, v191
	s_waitcnt lgkmcnt(0)
	v_add_f32_e32 v164, v164, v165
	ds_bpermute_b32 v165, v174, v164
	s_and_saveexec_b64 s[0:1], vcc
	s_xor_b64 s[0:1], exec, s[0:1]
	s_cbranch_execz .LBB0_1272
	v_cmp_lt_i32_e32 vcc, 1, v172
	s_and_saveexec_b64 s[30:31], vcc
	s_xor_b64 s[30:31], exec, s[30:31]
	s_cbranch_execz .LBB0_1259
	v_cmp_eq_u32_e32 vcc, 2, v172
	s_mov_b64 s[4:5], -1
	s_and_saveexec_b64 s[34:35], vcc
	v_add_f32_e32 v166, v182, v183
	s_xor_b64 s[4:5], exec, -1
	s_or_b64 exec, exec, s[34:35]
	s_and_b64 s[4:5], s[4:5], exec
